# attention: hipcc's packed-f32 v_pk_mul_f32 output rescale split into scalar v_mul_f32 (packed f32 is slower beside MFMAs)
# speedup vs baseline: 1.0036x; 1.0036x over previous
.LBB0_935:
	s_mov_b64 s[8:9], s[4:5]
	s_add_u32 s4, s8, 1
	s_addc_u32 s5, s9, 0
	s_cmp_ge_u32 s4, s11
	s_cselect_b64 s[6:7], -1, 0
	s_cmp_lt_u32 s4, s11
	s_cselect_b64 s[12:13], -1, 0
	v_cndmask_b32_e64 v32, 0, 1, s[12:13]
	v_mov_b32_e32 v33, s89
	v_lshl_add_u64 v[32:33], s[8:9], 0, v[32:33]
	v_lshlrev_b64 v[34:35], 16, v[32:33]
	v_lshl_add_u64 v[34:35], v[90:91], 0, v[34:35]
	v_lshlrev_b32_e32 v136, 6, v32
	s_waitcnt lgkmcnt(0)
	s_barrier
	s_waitcnt vmcnt(1)
	ds_write_b128 v94, v[80:83] offset:8192
	s_waitcnt vmcnt(0)
	ds_write_b128 v94, v[84:87] offset:17408
	s_waitcnt lgkmcnt(0)
	s_barrier
	v_lshl_add_u64 v[32:33], v[136:137], 1, v[92:93]
	global_load_dwordx4 v[80:83], v[34:35], off
	global_load_dwordx4 v[84:87], v[32:33], off
	v_cmp_le_i32_e32 vcc, s10, v98
	s_and_saveexec_b64 s[8:9], vcc
	s_cbranch_execz .LBB0_934
	s_add_i32 s101, s10, 94
	s_cmp_le_i32 s101, s100
	s_cbranch_scc1 .Latt_nomask
	ds_read_b128 v[32:35], v101 offset:8192
	ds_read_b128 v[36:39], v101 offset:8224
	v_add_u32_e32 v130, s10, v95
	v_cmp_le_i32_e32 vcc, v130, v96
	v_add_u32_e32 v131, 2, v130
	s_waitcnt lgkmcnt(1)
	v_mfma_f32_32x32x16_bf16 v[48:63], v[32:35], v[72:75], v[144:159]
	ds_read_b128 v[32:35], v101 offset:8256
	ds_read_b128 v[106:109], v101 offset:8288
	v_add_u32_e32 v132, 3, v130
	v_add_u32_e32 v133, 8, v130
	v_add_u32_e32 v134, 9, v130
	s_mov_b32 s12, 0xf149f2ca
	s_waitcnt lgkmcnt(2)
	v_mfma_f32_32x32x16_bf16 v[48:63], v[36:39], v[64:67], v[48:63]
	s_waitcnt lgkmcnt(1)
	v_mfma_f32_32x32x16_bf16 v[48:63], v[32:35], v[68:71], v[48:63]
	ds_read_b128 v[32:35], v101 offset:12800
	ds_read_b128 v[110:113], v101 offset:12832
	ds_read_b128 v[114:117], v101 offset:12864
	ds_read_b128 v[118:121], v101 offset:12896
	ds_read_b128 v[122:125], v104
	ds_read_b128 v[126:129], v104 offset:32
	s_waitcnt lgkmcnt(6)
	v_mfma_f32_32x32x16_bf16 v[48:63], v[106:109], v[76:79], v[48:63]
	s_waitcnt lgkmcnt(5)
	v_mfma_f32_32x32x16_bf16 v[32:47], v[32:35], v[72:75], v[144:159]
	s_nop 9
	s_waitcnt lgkmcnt(1)
	v_sub_f32_e32 v48, v48, v122
	v_sub_f32_e32 v49, v49, v123
	v_cndmask_b32_e32 v106, v187, v48, vcc
	v_cmp_lt_i32_e32 vcc, v130, v96
	v_sub_f32_e32 v50, v50, v124
	s_nop 0
	v_cndmask_b32_e32 v107, v187, v49, vcc
	v_cmp_le_i32_e32 vcc, v131, v96
	v_sub_f32_e32 v51, v51, v125
	s_nop 0
	v_cndmask_b32_e32 v108, v187, v50, vcc
	v_cmp_le_i32_e32 vcc, v132, v96
	s_waitcnt lgkmcnt(0)
	v_sub_f32_e32 v52, v52, v126
	v_cndmask_b32_e32 v109, v187, v51, vcc
	v_cmp_le_i32_e32 vcc, v133, v96
	v_sub_f32_e32 v53, v53, v127
	s_nop 0
	v_cndmask_b32_e32 v122, v187, v52, vcc
	v_cmp_le_i32_e32 vcc, v134, v96
	v_add_u32_e32 v50, 10, v130
	v_sub_f32_e32 v49, v54, v128
	v_cndmask_b32_e32 v123, v187, v53, vcc
	v_cmp_le_i32_e32 vcc, v50, v96
	v_max3_f32 v48, v106, s12, v107
	v_mfma_f32_32x32x16_bf16 v[32:47], v[110:113], v[64:67], v[32:47]
	v_cndmask_b32_e32 v110, v187, v49, vcc
	v_add_u32_e32 v50, 11, v130
	v_max3_f32 v48, v48, v108, v109
	v_sub_f32_e32 v49, v55, v129
	v_cmp_le_i32_e32 vcc, v50, v96
	v_max3_f32 v48, v48, v122, v123
	v_add_u32_e32 v113, 16, v130
	v_cndmask_b32_e32 v111, v187, v49, vcc
	v_max3_f32 v112, v48, v110, v111
	ds_read_b128 v[48:51], v104 offset:64
	ds_read_b128 v[52:55], v104 offset:96
	v_cmp_le_i32_e32 vcc, v113, v96
	v_mfma_f32_32x32x16_bf16 v[32:47], v[114:117], v[68:71], v[32:47]
	s_waitcnt lgkmcnt(1)
	v_sub_f32_e32 v48, v56, v48
	v_cndmask_b32_e32 v56, v187, v48, vcc
	v_sub_f32_e32 v48, v57, v49
	v_add_u32_e32 v49, 17, v130
	v_cmp_le_i32_e32 vcc, v49, v96
	v_sub_f32_e32 v49, v58, v50
	v_add_u32_e32 v50, 18, v130
	v_cndmask_b32_e32 v57, v187, v48, vcc
	v_cmp_le_i32_e32 vcc, v50, v96
	v_add_u32_e32 v50, 19, v130
	v_max3_f32 v48, v112, v56, v57
	v_cndmask_b32_e32 v58, v187, v49, vcc
	v_sub_f32_e32 v49, v59, v51
	v_cmp_le_i32_e32 vcc, v50, v96
	s_waitcnt lgkmcnt(0)
	v_sub_f32_e32 v50, v60, v52
	v_cndmask_b32_e32 v59, v187, v49, vcc
	v_add_u32_e32 v49, 24, v130
	v_cmp_le_i32_e32 vcc, v49, v96
	v_sub_f32_e32 v49, v61, v53
	s_nop 0
	v_cndmask_b32_e32 v60, v187, v50, vcc
	v_add_u32_e32 v50, 25, v130
	v_cmp_le_i32_e32 vcc, v50, v96
	v_max3_f32 v48, v48, v58, v59
	v_mfma_f32_32x32x16_bf16 v[32:47], v[118:121], v[76:79], v[32:47]
	v_cndmask_b32_e32 v61, v187, v49, vcc
	v_max3_f32 v52, v48, v60, v61
	v_add_u32_e32 v49, 26, v130
	v_sub_f32_e32 v48, v62, v54
	v_cmp_le_i32_e32 vcc, v49, v96
	v_add_u32_e32 v49, 27, v130
	v_add_u32_e32 v113, 32, v130
	v_cndmask_b32_e32 v62, v187, v48, vcc
	v_sub_f32_e32 v48, v63, v55
	v_cmp_le_i32_e32 vcc, v49, v96
	s_nop 1
	v_cndmask_b32_e32 v63, v187, v48, vcc
	ds_read_b128 v[48:51], v104 offset:128
	v_max3_f32 v112, v52, v62, v63
	ds_read_b128 v[52:55], v104 offset:160
	v_cmp_le_i32_e32 vcc, v113, v96
	v_add_u32_e32 v113, 48, v130
	s_waitcnt lgkmcnt(1)
	v_sub_f32_e32 v32, v32, v48
	v_cndmask_b32_e32 v48, v187, v32, vcc
	v_mov_b32_e32 v32, v33
	v_add_u32_e32 v33, 33, v130
	v_sub_f32_e32 v32, v32, v49
	v_cmp_le_i32_e32 vcc, v33, v96
	v_mov_b32_e32 v33, v34
	v_add_u32_e32 v34, 34, v130
	v_cndmask_b32_e32 v49, v187, v32, vcc
	v_sub_f32_e32 v33, v33, v50
	v_cmp_le_i32_e32 vcc, v34, v96
	v_add_u32_e32 v34, 35, v130
	v_max3_f32 v32, v112, v48, v49
	v_cndmask_b32_e32 v50, v187, v33, vcc
	v_sub_f32_e32 v33, v35, v51
	v_cmp_le_i32_e32 vcc, v34, v96
	s_waitcnt lgkmcnt(0)
	v_sub_f32_e32 v34, v36, v52
	v_cndmask_b32_e32 v51, v187, v33, vcc
	v_add_u32_e32 v33, 40, v130
	v_cmp_le_i32_e32 vcc, v33, v96
	v_sub_f32_e32 v33, v37, v53
	s_nop 0
	v_cndmask_b32_e32 v52, v187, v34, vcc
	v_add_u32_e32 v34, 41, v130
	v_cmp_le_i32_e32 vcc, v34, v96
	v_max3_f32 v32, v32, v50, v51
	s_nop 0
	v_cndmask_b32_e32 v53, v187, v33, vcc
	v_max3_f32 v36, v32, v52, v53
	v_add_u32_e32 v33, 42, v130
	v_sub_f32_e32 v32, v38, v54
	v_cmp_le_i32_e32 vcc, v33, v96
	v_add_u32_e32 v33, 43, v130
	s_nop 0
	v_cndmask_b32_e32 v54, v187, v32, vcc
	v_sub_f32_e32 v32, v39, v55
	v_cmp_le_i32_e32 vcc, v33, v96
	s_nop 1
	v_cndmask_b32_e32 v55, v187, v32, vcc
	ds_read_b128 v[32:35], v104 offset:192
	v_max3_f32 v112, v36, v54, v55
	ds_read_b128 v[36:39], v104 offset:224
	v_cmp_le_i32_e32 vcc, v113, v96
	s_waitcnt lgkmcnt(1)
	v_sub_f32_e32 v32, v40, v32
	v_sub_f32_e32 v33, v41, v33
	v_add_u32_e32 v40, 49, v130
	v_cndmask_b32_e32 v32, v187, v32, vcc
	v_cmp_le_i32_e32 vcc, v40, v96
	v_sub_f32_e32 v34, v42, v34
	v_add_u32_e32 v41, 50, v130
	v_cndmask_b32_e32 v33, v187, v33, vcc
	v_cmp_le_i32_e32 vcc, v41, v96
	v_sub_f32_e32 v35, v43, v35
	v_add_u32_e32 v41, 51, v130
	v_cndmask_b32_e32 v34, v187, v34, vcc
	v_cmp_le_i32_e32 vcc, v41, v96
	v_add_u32_e32 v41, 56, v130
	s_nop 0
	v_cndmask_b32_e32 v35, v187, v35, vcc
	v_cmp_le_i32_e32 vcc, v41, v96
	s_waitcnt lgkmcnt(0)
	v_sub_f32_e32 v36, v44, v36
	v_sub_f32_e32 v37, v45, v37
	v_add_u32_e32 v41, 57, v130
	v_max3_f32 v40, v112, v32, v33
	v_cndmask_b32_e32 v36, v187, v36, vcc
	v_cmp_le_i32_e32 vcc, v41, v96
	v_max3_f32 v40, v40, v34, v35
	s_nop 0
	v_cndmask_b32_e32 v112, v187, v37, vcc
	v_max3_f32 v37, v40, v36, v112
	v_sub_f32_e32 v38, v46, v38
	v_add_u32_e32 v40, 58, v130
	v_cmp_le_i32_e32 vcc, v40, v96
	s_nop 1
	v_cndmask_b32_e32 v46, v187, v38, vcc
	v_sub_f32_e32 v38, v47, v39
	v_add_u32_e32 v39, 59, v130
	v_cmp_le_i32_e32 vcc, v39, v96
	s_nop 1
	v_cndmask_b32_e32 v47, v187, v38, vcc
	v_max3_f32 v37, v37, v46, v47
	ds_bpermute_b32 v38, v99, v37
	s_waitcnt lgkmcnt(0)
	v_max3_f32 v113, v105, v37, v38
	s_mov_b32 s99, 0x3fb8aa3b
	v_mul_f32_e32 v250, 0xbfb8aa3b, v113
	v_fma_f32 v38, v106, s99, v250
	v_exp_f32_e32 v38, v38
	v_fma_f32 v39, v107, s99, v250
	v_exp_f32_e32 v39, v39
	v_fma_f32 v40, v108, s99, v250
	v_exp_f32_e32 v40, v40
	v_fma_f32 v41, v109, s99, v250
	v_exp_f32_e32 v41, v41
	v_fma_f32 v43, v122, s99, v250
	v_add_f32_e32 v42, 0, v38
	v_exp_f32_e32 v43, v43
	v_fma_f32 v44, v123, s99, v250
	v_sub_f32_e32 v37, v105, v113
	v_add_f32_e32 v42, v39, v42
	v_exp_f32_e32 v44, v44
	v_fma_f32 v45, v110, s99, v250
	v_add_f32_e32 v42, v40, v42
	v_exp_f32_e32 v45, v45
	v_fma_f32 v105, v111, s99, v250
	v_add_f32_e32 v42, v41, v42
	v_exp_f32_e32 v105, v105
	v_fma_f32 v56, v56, s99, v250
	v_add_f32_e32 v42, v43, v42
	v_exp_f32_e32 v56, v56
	v_fma_f32 v57, v57, s99, v250
	v_add_f32_e32 v42, v44, v42
	v_exp_f32_e32 v57, v57
	v_fma_f32 v58, v58, s99, v250
	v_add_f32_e32 v42, v45, v42
	v_exp_f32_e32 v58, v58
	v_fma_f32 v59, v59, s99, v250
	v_add_f32_e32 v42, v105, v42
	v_exp_f32_e32 v59, v59
	v_fma_f32 v60, v60, s99, v250
	v_add_f32_e32 v42, v56, v42
	v_exp_f32_e32 v60, v60
	v_fma_f32 v61, v61, s99, v250
	v_add_f32_e32 v42, v57, v42
	v_exp_f32_e32 v61, v61
	v_fma_f32 v62, v62, s99, v250
	v_add_f32_e32 v42, v58, v42
	v_exp_f32_e32 v62, v62
	v_fma_f32 v63, v63, s99, v250
	v_add_f32_e32 v42, v59, v42
	v_exp_f32_e32 v63, v63
	v_add_f32_e32 v42, v60, v42
	v_add_f32_e32 v42, v61, v42
	v_add_f32_e32 v42, v62, v42
	v_add_f32_e32 v106, v63, v42
	v_fma_f32 v42, v48, s99, v250
	v_exp_f32_e32 v48, v42
	v_fma_f32 v32, v32, s99, v250
	v_fma_f32 v42, v49, s99, v250
	v_exp_f32_e32 v107, v32
	v_exp_f32_e32 v49, v42
	v_fma_f32 v32, v33, s99, v250
	v_fma_f32 v42, v50, s99, v250
	v_exp_f32_e32 v33, v32
	v_exp_f32_e32 v50, v42
	v_fma_f32 v32, v34, s99, v250
	v_fma_f32 v42, v51, s99, v250
	v_exp_f32_e32 v108, v32
	v_mul_f32_e32 v37, 0x3fb8aa3b, v37
	v_exp_f32_e32 v51, v42
	v_fma_f32 v32, v35, s99, v250
	v_fma_f32 v34, v36, s99, v250
	v_fma_f32 v42, v52, s99, v250
	v_exp_f32_e32 v109, v32
	v_exp_f32_e32 v32, v37
	v_exp_f32_e32 v110, v34
	ds_read2_b64 v[34:37], v102 offset0:128 offset1:130
	v_exp_f32_e32 v52, v42
	v_fma_f32 v42, v53, s99, v250
	v_exp_f32_e32 v53, v42
	v_fma_f32 v42, v54, s99, v250
	v_exp_f32_e32 v54, v42
	v_fma_f32 v42, v55, s99, v250
	v_exp_f32_e32 v55, v42
	v_cvt_pk_bf16_f32 v38, v38, v39
	v_cvt_pk_bf16_f32 v39, v40, v41
	v_cvt_pk_bf16_f32 v40, v43, v44
	v_cvt_pk_bf16_f32 v41, v45, v105
	ds_read2_b64 v[42:45], v103 offset0:192 offset1:194
	v_mul_f32_e32 v30, v32, v30
	v_mul_f32_e32 v31, v32, v31
	v_mul_f32_e32 v28, v32, v28
	v_mul_f32_e32 v29, v32, v29
	v_mul_f32_e32 v26, v32, v26
	v_mul_f32_e32 v27, v32, v27
	v_mul_f32_e32 v24, v32, v24
	v_mul_f32_e32 v25, v32, v25
	v_mul_f32_e32 v22, v32, v22
	v_mul_f32_e32 v23, v32, v23
	v_mul_f32_e32 v20, v32, v20
	v_mul_f32_e32 v21, v32, v21
	v_mul_f32_e32 v18, v32, v18
	v_mul_f32_e32 v19, v32, v19
	v_mul_f32_e32 v16, v32, v16
	v_mul_f32_e32 v17, v32, v17
	v_mul_f32_e32 v14, v32, v14
	v_mul_f32_e32 v15, v32, v15
	v_mul_f32_e32 v12, v32, v12
	v_mul_f32_e32 v13, v32, v13
	s_waitcnt lgkmcnt(1)
	v_mfma_f32_32x32x16_bf16 v[16:31], v[34:37], v[38:41], v[16:31]
	ds_read2_b64 v[34:37], v102 offset0:132 offset1:134
	v_mul_f32_e64 v10, v10, v32
	v_mul_f32_e64 v11, v11, v32
	v_mul_f32_e64 v8, v8, v32
	v_mul_f32_e64 v9, v9, v32
	v_mul_f32_e32 v6, v32, v6
	v_mul_f32_e32 v7, v32, v7
	v_mul_f32_e32 v4, v32, v4
	v_mul_f32_e32 v5, v32, v5
	v_mul_f32_e32 v2, v32, v2
	v_mul_f32_e32 v3, v32, v3
	v_mul_f32_e32 v0, v32, v0
	v_mul_f32_e32 v1, v32, v1
	s_waitcnt lgkmcnt(1)
	s_nop 0
	v_mfma_f32_32x32x16_bf16 v[0:15], v[42:45], v[38:41], v[0:15]
	v_fma_f32 v105, v112, s99, v250
	v_cvt_pk_bf16_f32 v38, v56, v57
	v_cvt_pk_bf16_f32 v39, v58, v59
	v_cvt_pk_bf16_f32 v40, v60, v61
	v_cvt_pk_bf16_f32 v41, v62, v63
	ds_read2_b64 v[42:45], v103 offset0:196 offset1:198
	v_add_f32_e32 v57, v48, v106
	s_waitcnt lgkmcnt(1)
	v_mfma_f32_32x32x16_bf16 v[16:31], v[34:37], v[38:41], v[16:31]
	v_fma_f32 v34, v46, s99, v250
	v_exp_f32_e32 v46, v34
	v_fma_f32 v47, v47, s99, v250
	ds_read2_b64 v[34:37], v102 offset0:136 offset1:138
	v_exp_f32_e32 v56, v105
	s_waitcnt lgkmcnt(1)
	v_mfma_f32_32x32x16_bf16 v[0:15], v[42:45], v[38:41], v[0:15]
	ds_read2_b64 v[42:45], v103 offset0:200 offset1:202
	v_cvt_pk_bf16_f32 v38, v48, v49
	v_cvt_pk_bf16_f32 v39, v50, v51
	v_cvt_pk_bf16_f32 v40, v52, v53
	v_cvt_pk_bf16_f32 v41, v54, v55
	v_exp_f32_e32 v47, v47
	v_mov_b32_e32 v105, v113
	s_waitcnt lgkmcnt(1)
	v_mfma_f32_32x32x16_bf16 v[16:31], v[34:37], v[38:41], v[16:31]
	v_add_f32_e32 v34, v49, v57
	v_add_f32_e32 v34, v50, v34
	v_add_f32_e32 v34, v51, v34
	v_add_f32_e32 v34, v52, v34
	v_add_f32_e32 v34, v53, v34
	v_add_f32_e32 v48, v54, v34
	ds_read2_b64 v[34:37], v102 offset0:140 offset1:142
	s_waitcnt lgkmcnt(1)
	v_mfma_f32_32x32x16_bf16 v[0:15], v[42:45], v[38:41], v[0:15]
	ds_read2_b64 v[42:45], v103 offset0:204 offset1:206
	v_add_f32_e32 v38, v55, v48
	v_add_f32_e32 v48, v107, v38
	v_cvt_pk_bf16_f32 v38, v107, v33
	v_cvt_pk_bf16_f32 v39, v108, v109
	v_cvt_pk_bf16_f32 v40, v110, v56
	v_cvt_pk_bf16_f32 v41, v46, v47
	v_add_f32_e32 v33, v33, v48
	v_add_f32_e32 v33, v108, v33
	s_waitcnt lgkmcnt(1)
	v_mfma_f32_32x32x16_bf16 v[16:31], v[34:37], v[38:41], v[16:31]
	v_add_f32_e32 v33, v109, v33
	v_add_f32_e32 v33, v110, v33
	v_add_f32_e32 v33, v56, v33
	v_add_f32_e32 v33, v46, v33
	v_add_f32_e32 v33, v47, v33
	v_fmac_f32_e32 v33, v100, v32
	v_mov_b32_e32 v100, v33
	s_waitcnt lgkmcnt(0)
	v_mfma_f32_32x32x16_bf16 v[0:15], v[42:45], v[38:41], v[0:15]
	s_branch .LBB0_934
.Latt_nomask:
	ds_read_b128 v[32:35], v101 offset:8192
	ds_read_b128 v[36:39], v101 offset:8224
	s_waitcnt lgkmcnt(1)
	v_mfma_f32_32x32x16_bf16 v[48:63], v[32:35], v[72:75], v[144:159]
	ds_read_b128 v[32:35], v101 offset:8256
	ds_read_b128 v[106:109], v101 offset:8288
	s_mov_b32 s12, 0xf149f2ca
	s_waitcnt lgkmcnt(2)
	v_mfma_f32_32x32x16_bf16 v[48:63], v[36:39], v[64:67], v[48:63]
	s_waitcnt lgkmcnt(1)
	v_mfma_f32_32x32x16_bf16 v[48:63], v[32:35], v[68:71], v[48:63]
	ds_read_b128 v[32:35], v101 offset:12800
	ds_read_b128 v[110:113], v101 offset:12832
	ds_read_b128 v[114:117], v101 offset:12864
	ds_read_b128 v[118:121], v101 offset:12896
	ds_read_b128 v[122:125], v104
	ds_read_b128 v[126:129], v104 offset:32
	s_waitcnt lgkmcnt(6)
	v_mfma_f32_32x32x16_bf16 v[48:63], v[106:109], v[76:79], v[48:63]
	s_waitcnt lgkmcnt(5)
	v_mfma_f32_32x32x16_bf16 v[32:47], v[32:35], v[72:75], v[144:159]
	s_nop 9
	s_waitcnt lgkmcnt(1)
	v_sub_f32_e32 v106, v48, v122
	v_sub_f32_e32 v107, v49, v123
	v_sub_f32_e32 v108, v50, v124
	v_sub_f32_e32 v109, v51, v125
	s_waitcnt lgkmcnt(0)
	v_sub_f32_e32 v122, v52, v126
	v_sub_f32_e32 v123, v53, v127
	v_sub_f32_e32 v49, v54, v128
	v_max3_f32 v48, v106, s12, v107
	v_mfma_f32_32x32x16_bf16 v[32:47], v[110:113], v[64:67], v[32:47]
	v_mov_b32_e32 v110, v49
	v_max3_f32 v48, v48, v108, v109
	v_sub_f32_e32 v111, v55, v129
	v_max3_f32 v48, v48, v122, v123
	v_max3_f32 v112, v48, v110, v111
	ds_read_b128 v[48:51], v104 offset:64
	ds_read_b128 v[52:55], v104 offset:96
	v_mfma_f32_32x32x16_bf16 v[32:47], v[114:117], v[68:71], v[32:47]
	s_waitcnt lgkmcnt(1)
	v_sub_f32_e32 v56, v56, v48
	v_sub_f32_e32 v57, v57, v49
	v_sub_f32_e32 v58, v58, v50
	v_max3_f32 v48, v112, v56, v57
	v_sub_f32_e32 v59, v59, v51
	s_waitcnt lgkmcnt(0)
	v_sub_f32_e32 v60, v60, v52
	v_sub_f32_e32 v61, v61, v53
	v_max3_f32 v48, v48, v58, v59
	v_mfma_f32_32x32x16_bf16 v[32:47], v[118:121], v[76:79], v[32:47]
	v_max3_f32 v52, v48, v60, v61
	v_sub_f32_e32 v62, v62, v54
	v_sub_f32_e32 v63, v63, v55
	s_nop 6
	ds_read_b128 v[48:51], v104 offset:128
	v_max3_f32 v112, v52, v62, v63
	ds_read_b128 v[52:55], v104 offset:160
	s_waitcnt lgkmcnt(1)
	v_sub_f32_e32 v48, v32, v48
	v_sub_f32_e32 v49, v33, v49
	v_sub_f32_e32 v50, v34, v50
	v_max3_f32 v32, v112, v48, v49
	v_sub_f32_e32 v51, v35, v51
	s_waitcnt lgkmcnt(0)
	v_sub_f32_e32 v52, v36, v52
	v_sub_f32_e32 v53, v37, v53
	v_max3_f32 v32, v32, v50, v51
	s_nop 0
	v_max3_f32 v36, v32, v52, v53
	v_sub_f32_e32 v54, v38, v54
	s_nop 0
	v_sub_f32_e32 v55, v39, v55
	s_nop 1
	ds_read_b128 v[32:35], v104 offset:192
	v_max3_f32 v112, v36, v54, v55
	ds_read_b128 v[36:39], v104 offset:224
	s_waitcnt lgkmcnt(1)
	v_sub_f32_e32 v32, v40, v32
	v_sub_f32_e32 v33, v41, v33
	v_sub_f32_e32 v34, v42, v34
	v_sub_f32_e32 v35, v43, v35
	s_waitcnt lgkmcnt(0)
	v_sub_f32_e32 v36, v44, v36
	v_sub_f32_e32 v37, v45, v37
	v_max3_f32 v40, v112, v32, v33
	v_max3_f32 v40, v40, v34, v35
	s_nop 0
	v_mov_b32_e32 v112, v37
	v_max3_f32 v37, v40, v36, v112
	v_sub_f32_e32 v46, v46, v38
	s_nop 1
	v_sub_f32_e32 v47, v47, v39
	s_nop 1
	v_max3_f32 v37, v37, v46, v47
	ds_bpermute_b32 v38, v99, v37
	s_waitcnt lgkmcnt(0)
	v_max3_f32 v113, v105, v37, v38
	s_mov_b32 s99, 0x3fb8aa3b
	v_mul_f32_e32 v250, 0xbfb8aa3b, v113
	v_fma_f32 v38, v106, s99, v250
	v_exp_f32_e32 v38, v38
	v_fma_f32 v39, v107, s99, v250
	v_exp_f32_e32 v39, v39
	v_fma_f32 v40, v108, s99, v250
	v_exp_f32_e32 v40, v40
	v_fma_f32 v41, v109, s99, v250
	v_exp_f32_e32 v41, v41
	v_fma_f32 v43, v122, s99, v250
	v_add_f32_e32 v42, 0, v38
	v_exp_f32_e32 v43, v43
	v_fma_f32 v44, v123, s99, v250
	v_sub_f32_e32 v37, v105, v113
	v_add_f32_e32 v42, v39, v42
	v_exp_f32_e32 v44, v44
	v_fma_f32 v45, v110, s99, v250
	v_add_f32_e32 v42, v40, v42
	v_exp_f32_e32 v45, v45
	v_fma_f32 v105, v111, s99, v250
	v_add_f32_e32 v42, v41, v42
	v_exp_f32_e32 v105, v105
	v_fma_f32 v56, v56, s99, v250
	v_add_f32_e32 v42, v43, v42
	v_exp_f32_e32 v56, v56
	v_fma_f32 v57, v57, s99, v250
	v_add_f32_e32 v42, v44, v42
	v_exp_f32_e32 v57, v57
	v_fma_f32 v58, v58, s99, v250
	v_add_f32_e32 v42, v45, v42
	v_exp_f32_e32 v58, v58
	v_fma_f32 v59, v59, s99, v250
	v_add_f32_e32 v42, v105, v42
	v_exp_f32_e32 v59, v59
	v_fma_f32 v60, v60, s99, v250
	v_add_f32_e32 v42, v56, v42
	v_exp_f32_e32 v60, v60
	v_fma_f32 v61, v61, s99, v250
	v_add_f32_e32 v42, v57, v42
	v_exp_f32_e32 v61, v61
	v_fma_f32 v62, v62, s99, v250
	v_add_f32_e32 v42, v58, v42
	v_exp_f32_e32 v62, v62
	v_fma_f32 v63, v63, s99, v250
	v_add_f32_e32 v42, v59, v42
	v_exp_f32_e32 v63, v63
	v_add_f32_e32 v42, v60, v42
	v_add_f32_e32 v42, v61, v42
	v_add_f32_e32 v42, v62, v42
	v_add_f32_e32 v106, v63, v42
	v_fma_f32 v42, v48, s99, v250
	v_exp_f32_e32 v48, v42
	v_fma_f32 v32, v32, s99, v250
	v_fma_f32 v42, v49, s99, v250
	v_exp_f32_e32 v107, v32
	v_exp_f32_e32 v49, v42
	v_fma_f32 v32, v33, s99, v250
	v_fma_f32 v42, v50, s99, v250
	v_exp_f32_e32 v33, v32
	v_exp_f32_e32 v50, v42
	v_fma_f32 v32, v34, s99, v250
	v_fma_f32 v42, v51, s99, v250
	v_exp_f32_e32 v108, v32
	v_mul_f32_e32 v37, 0x3fb8aa3b, v37
	v_exp_f32_e32 v51, v42
	v_fma_f32 v32, v35, s99, v250
	v_fma_f32 v34, v36, s99, v250
	v_fma_f32 v42, v52, s99, v250
	v_exp_f32_e32 v109, v32
	v_exp_f32_e32 v32, v37
	v_exp_f32_e32 v110, v34
	ds_read2_b64 v[34:37], v102 offset0:128 offset1:130
	v_exp_f32_e32 v52, v42
	v_fma_f32 v42, v53, s99, v250
	v_exp_f32_e32 v53, v42
	v_fma_f32 v42, v54, s99, v250
	v_exp_f32_e32 v54, v42
	v_fma_f32 v42, v55, s99, v250
	v_exp_f32_e32 v55, v42
	v_cvt_pk_bf16_f32 v38, v38, v39
	v_cvt_pk_bf16_f32 v39, v40, v41
	v_cvt_pk_bf16_f32 v40, v43, v44
	v_cvt_pk_bf16_f32 v41, v45, v105
	ds_read2_b64 v[42:45], v103 offset0:192 offset1:194
	v_mul_f32_e32 v30, v32, v30
	v_mul_f32_e32 v31, v32, v31
	v_mul_f32_e32 v28, v32, v28
	v_mul_f32_e32 v29, v32, v29
	v_mul_f32_e32 v26, v32, v26
	v_mul_f32_e32 v27, v32, v27
	v_mul_f32_e32 v24, v32, v24
	v_mul_f32_e32 v25, v32, v25
	v_mul_f32_e32 v22, v32, v22
	v_mul_f32_e32 v23, v32, v23
	v_mul_f32_e32 v20, v32, v20
	v_mul_f32_e32 v21, v32, v21
	v_mul_f32_e32 v18, v32, v18
	v_mul_f32_e32 v19, v32, v19
	v_mul_f32_e32 v16, v32, v16
	v_mul_f32_e32 v17, v32, v17
	v_mul_f32_e32 v14, v32, v14
	v_mul_f32_e32 v15, v32, v15
	v_mul_f32_e32 v12, v32, v12
	v_mul_f32_e32 v13, v32, v13
	s_waitcnt lgkmcnt(1)
	v_mfma_f32_32x32x16_bf16 v[16:31], v[34:37], v[38:41], v[16:31]
	ds_read2_b64 v[34:37], v102 offset0:132 offset1:134
	v_mul_f32_e64 v10, v10, v32
	v_mul_f32_e64 v11, v11, v32
	v_mul_f32_e64 v8, v8, v32
	v_mul_f32_e64 v9, v9, v32
	v_mul_f32_e32 v6, v32, v6
	v_mul_f32_e32 v7, v32, v7
	v_mul_f32_e32 v4, v32, v4
	v_mul_f32_e32 v5, v32, v5
	v_mul_f32_e32 v2, v32, v2
	v_mul_f32_e32 v3, v32, v3
	v_mul_f32_e32 v0, v32, v0
	v_mul_f32_e32 v1, v32, v1
	s_waitcnt lgkmcnt(1)
	s_nop 0
	v_mfma_f32_32x32x16_bf16 v[0:15], v[42:45], v[38:41], v[0:15]
	v_fma_f32 v105, v112, s99, v250
	v_cvt_pk_bf16_f32 v38, v56, v57
	v_cvt_pk_bf16_f32 v39, v58, v59
	v_cvt_pk_bf16_f32 v40, v60, v61
	v_cvt_pk_bf16_f32 v41, v62, v63
	ds_read2_b64 v[42:45], v103 offset0:196 offset1:198
	v_add_f32_e32 v57, v48, v106
	s_waitcnt lgkmcnt(1)
	v_mfma_f32_32x32x16_bf16 v[16:31], v[34:37], v[38:41], v[16:31]
	v_fma_f32 v34, v46, s99, v250
	v_exp_f32_e32 v46, v34
	v_fma_f32 v47, v47, s99, v250
	ds_read2_b64 v[34:37], v102 offset0:136 offset1:138
	v_exp_f32_e32 v56, v105
	s_waitcnt lgkmcnt(1)
	v_mfma_f32_32x32x16_bf16 v[0:15], v[42:45], v[38:41], v[0:15]
	ds_read2_b64 v[42:45], v103 offset0:200 offset1:202
	v_cvt_pk_bf16_f32 v38, v48, v49
	v_cvt_pk_bf16_f32 v39, v50, v51
	v_cvt_pk_bf16_f32 v40, v52, v53
	v_cvt_pk_bf16_f32 v41, v54, v55
	v_exp_f32_e32 v47, v47
	v_mov_b32_e32 v105, v113
	s_waitcnt lgkmcnt(1)
	v_mfma_f32_32x32x16_bf16 v[16:31], v[34:37], v[38:41], v[16:31]
	v_add_f32_e32 v34, v49, v57
	v_add_f32_e32 v34, v50, v34
	v_add_f32_e32 v34, v51, v34
	v_add_f32_e32 v34, v52, v34
	v_add_f32_e32 v34, v53, v34
	v_add_f32_e32 v48, v54, v34
	ds_read2_b64 v[34:37], v102 offset0:140 offset1:142
	s_waitcnt lgkmcnt(1)
	v_mfma_f32_32x32x16_bf16 v[0:15], v[42:45], v[38:41], v[0:15]
	ds_read2_b64 v[42:45], v103 offset0:204 offset1:206
	v_add_f32_e32 v38, v55, v48
	v_add_f32_e32 v48, v107, v38
	v_cvt_pk_bf16_f32 v38, v107, v33
	v_cvt_pk_bf16_f32 v39, v108, v109
	v_cvt_pk_bf16_f32 v40, v110, v56
	v_cvt_pk_bf16_f32 v41, v46, v47
	v_add_f32_e32 v33, v33, v48
	v_add_f32_e32 v33, v108, v33
	s_waitcnt lgkmcnt(1)
	v_mfma_f32_32x32x16_bf16 v[16:31], v[34:37], v[38:41], v[16:31]
	v_add_f32_e32 v33, v109, v33
	v_add_f32_e32 v33, v110, v33
	v_add_f32_e32 v33, v56, v33
	v_add_f32_e32 v33, v46, v33
	v_add_f32_e32 v33, v47, v33
	v_fmac_f32_e32 v33, v100, v32
	v_mov_b32_e32 v100, v33
	s_waitcnt lgkmcnt(0)
	v_mfma_f32_32x32x16_bf16 v[0:15], v[42:45], v[38:41], v[0:15]
	s_branch .LBB0_934
